# v22 + hand-written pipelined f32->bf16 transposing copy loop at the two idle-fill sites; all gate/up copy items of layer 0 made in the q-projection phase's idle workgroups, all of layer 1 in the compr
# baseline (speedup 1.0000x reference)
.LBB0_16:
	v_writelane_b32 v251, s95, 48
	s_andn2_b64 vcc, exec, s[0:1]
	v_writelane_b32 v251, s97, 49
	s_cbranch_vccnz .LBB0_538
	v_readlane_b32 s2, v251, 2
	v_readlane_b32 s3, v251, 3
	v_mov_b32 v1, 0
	s_and_b32 s85, s54, 0xffffffc0
	v_mbcnt_lo_u32_b32 v1, -1, v1
	v_mbcnt_hi_u32_b32 v2, -1, v1
	s_lshl_b32 s27, s95, 3
	s_lshl_b32 s4, s97, 3
	v_add_u32_e32 v3, s85, v2
	s_cmpk_eq_i32 s97, 0x100
	v_readfirstlane_b32 s29, v3
	s_cselect_b32 s11, 0x5600, 0
	s_ashr_i32 s28, s29, 6
	s_mul_i32 s0, s28, 0x2100
	s_sub_i32 s5, 0x5600, s11
	s_lshl_b32 s96, s97, 9
	v_and_b32_e32 v1, 63, v2
	s_add_i32 s10, s0, 0
	s_add_i32 s26, s28, s27
	s_movk_i32 s13, 0x5600
	s_cmp_ge_i32 s26, s5
	v_lshrrev_b32_e32 v77, 4, v1
	v_lshlrev_b32_e32 v78, 2, v1
	v_and_b32_e32 v76, 7, v2
	v_lshrrev_b32_e32 v88, 3, v1
	s_mov_b32 s12, s26
	s_cbranch_scc1 .LBB0_84
	v_readlane_b32 s36, v251, 16
	v_mov_b32_e32 v2, 0
	v_readlane_b32 s44, v251, 24
	v_readlane_b32 s45, v251, 25
	v_lshlrev_b32_e32 v4, 4, v76
	v_mov_b32_e32 v5, v2
	s_cmp_lg_u64 s[44:45], 0
	v_lshl_add_u64 v[4:5], s[2:3], 0, v[4:5]
	s_mov_b64 s[0:1], 0x8c00000
	s_cselect_b64 s[6:7], -1, 0
	v_and_b32_e32 v79, 60, v78
	v_lshrrev_b32_e32 v81, 3, v1
	v_lshl_add_u64 v[70:71], v[4:5], 0, s[0:1]
	s_add_i32 s0, s11, s28
	v_lshl_add_u32 v3, v79, 2, s10
	v_mul_u32_u24_e32 v6, 0x104, v77
	v_mul_u32_u24_e32 v7, 0x410, v76
	v_lshlrev_b32_e32 v4, 2, v81
	s_add_i32 s0, s0, s27
	v_lshlrev_b32_e32 v80, 1, v77
	v_add3_u32 v82, s10, v7, v4
	v_or_b32_e32 v83, 8, v81
	v_or_b32_e32 v84, 16, v81
	v_or_b32_e32 v85, 24, v81
	v_or_b32_e32 v86, 32, v81
	v_or_b32_e32 v87, 40, v81
	v_or_b32_e32 v89, 48, v81
	v_or_b32_e32 v90, 56, v81
	s_lshl_b32 s14, s0, 6
	s_mov_b32 s15, 0x15800
	v_add_u32_e32 v91, v3, v6
	s_mov_b32 s12, s26
	v_readlane_b32 s37, v251, 17
	v_readlane_b32 s38, v251, 18
	v_readlane_b32 s39, v251, 19
	v_readlane_b32 s40, v251, 20
	v_readlane_b32 s41, v251, 21
	v_readlane_b32 s42, v251, 22
	v_readlane_b32 s43, v251, 23
	v_readlane_b32 s46, v251, 26
	v_readlane_b32 s47, v251, 27
	v_readlane_b32 s48, v251, 28
	v_readlane_b32 s49, v251, 29
	v_readlane_b32 s50, v251, 30
	v_readlane_b32 s51, v251, 31
	s_branch .LBB0_20

.LBB0_680:
	s_lshr_b32 s11, s54, 6
	s_cmpk_lt_i32 s95, 0x700
	s_cselect_b64 s[0:1], -1, 0
	v_writelane_b32 v252, s0, 9
	s_ashr_i32 s81, s95, 31
	s_ashr_i32 s14, s97, 31
	v_writelane_b32 v252, s1, 10
	s_lshr_b32 s0, s81, 29
	s_add_i32 s12, s95, s0
	s_and_b32 s1, s12, -8
	s_ashr_i32 s0, s12, 3
	s_sub_i32 s1, s95, s1
	v_readlane_b32 s16, v251, 2
	v_readlane_b32 s17, v251, 3
	s_add_u32 s2, s16, 0x4200
	s_addc_u32 s3, s17, 0
	v_writelane_b32 v251, s2, 63
	s_lshl_b32 s87, s55, 8
	v_readlane_b32 s36, v251, 16
	v_writelane_b32 v252, s3, 0
	s_add_u32 s2, s56, s87
	s_addc_u32 s3, s57, 0
	s_add_u32 s4, s2, 0x1400
	s_addc_u32 s5, s3, 0
	v_writelane_b32 v252, s4, 11
	s_add_u32 s2, s2, 0x2400
	s_addc_u32 s3, s3, 0
	v_writelane_b32 v252, s5, 12
	v_writelane_b32 v252, s2, 13
	v_readlane_b32 s44, v251, 24
	v_readlane_b32 s45, v251, 25
	v_writelane_b32 v252, s3, 14
	s_add_u32 s2, s16, 0x7400
	s_addc_u32 s3, s17, 0
	v_writelane_b32 v252, s2, 15
	s_mov_b32 s77, 0
	v_readlane_b32 s42, v251, 22
	v_writelane_b32 v252, s3, 16
	s_add_u32 s2, s16, 0x7500
	s_addc_u32 s3, s17, 0
	v_writelane_b32 v252, s2, 17
	s_cmp_lt_i32 s95, 64
	v_readlane_b32 s43, v251, 23
	v_writelane_b32 v252, s3, 18
	s_cselect_b64 s[2:3], -1, 0
	s_lshl_b32 s9, s1, 3
	v_writelane_b32 v252, s2, 19
	s_cmp_gt_i32 s95, 63
	v_readlane_b32 s50, v251, 30
	v_writelane_b32 v252, s3, 20
	s_cselect_b64 s[2:3], -1, 0
	v_writelane_b32 v252, s2, 21
	v_readlane_b32 s51, v251, 31
	v_readlane_b32 s18, v251, 50
	v_writelane_b32 v252, s3, 22
	s_sub_i32 s2, s95, 64
	s_cmp_lt_u32 s2, 64
	v_writelane_b32 v252, s2, 23
	s_cselect_b64 s[2:3], -1, 0
	s_lshl_b32 s19, s95, 3
	s_and_b32 s7, s19, 56
	s_bfe_u32 s8, s95, 0x30003
	v_writelane_b32 v252, s2, 24
	s_cmpk_eq_i32 s97, 0x100
	v_readlane_b32 s37, v251, 17
	v_writelane_b32 v252, s3, 25
	s_cselect_b64 s[2:3], -1, 0
	s_and_b64 s[4:5], s[2:3], exec
	s_cselect_b32 s6, 0x80, 0
	s_sub_i32 s4, s97, s6
	s_cmp_ge_i32 s95, s6
	s_cselect_b64 s[20:21], -1, 0
	v_writelane_b32 v252, s20, 26
	s_mul_i32 s5, s11, 0x2100
	s_add_i32 s5, s5, 0
	v_writelane_b32 v252, s21, 27
	v_writelane_b32 v252, s5, 28
	s_sub_i32 s5, s95, s6
	s_lshl_b32 s5, s5, 3
	s_add_i32 s28, s5, s11
	s_cmpk_lt_i32 s28, 0x5600
	s_cselect_b64 s[20:21], -1, 0
	v_writelane_b32 v252, s20, 29
	v_readlane_b32 s38, v251, 18
	v_readlane_b32 s39, v251, 19
	v_writelane_b32 v252, s21, 30
	v_readlane_b32 s20, v251, 8
	v_readlane_b32 s22, v251, 10
	v_readlane_b32 s23, v251, 11
	s_add_u32 s22, s22, 0x15800000
	s_addc_u32 s23, s23, 0
	s_add_u32 s70, s44, 0x8000
	v_writelane_b32 v252, s22, 5
	s_addc_u32 s71, s45, 0
	s_lshl_b32 s4, s4, 3
	v_writelane_b32 v252, s23, 6
	s_cmp_lt_i32 s95, 32
	v_writelane_b32 v252, s4, 31
	s_cselect_b64 s[4:5], -1, 0
	v_writelane_b32 v252, s4, 32
	s_lshl_b32 s10, s1, 2
	v_readlane_b32 s21, v251, 9
	v_writelane_b32 v252, s5, 33
	s_add_u32 s4, s16, 0x1000
	s_addc_u32 s5, s17, 0
	v_writelane_b32 v252, s4, 34
	s_cmpk_lt_i32 s95, 0x800
	v_readlane_b32 s24, v251, 12
	v_writelane_b32 v252, s5, 35
	s_cselect_b64 s[4:5], -1, 0
	v_writelane_b32 v252, s4, 36
	s_and_b32 s13, s1, 3
	s_add_i32 s76, s1, 32
	v_writelane_b32 v252, s5, 37
	s_lshl_b32 s5, s12, 2
	s_and_b32 s12, s5, 0xffffffe0
	s_ashr_i32 s4, s1, 2
	s_sub_i32 s15, 0x1fe0, s12
	s_ashr_i32 s5, s4, 31
	v_writelane_b32 v252, s15, 38
	s_ashr_i32 s15, s15, 31
	v_writelane_b32 v252, s15, 39
	s_lshl_b64 s[4:5], s[4:5], 26
	v_writelane_b32 v252, s4, 40
	s_add_i32 s22, s11, s19
	v_readlane_b32 s25, v251, 13
	v_writelane_b32 v252, s5, 41
	s_lshl_b32 s4, s13, 10
	v_writelane_b32 v252, s4, 42
	s_lshl_b64 s[4:5], s[76:77], 21
	v_writelane_b32 v252, s4, 43
	v_readlane_b32 s26, v251, 14
	v_readlane_b32 s27, v251, 15
	v_writelane_b32 v252, s5, 44
	s_sub_i32 s4, 0x1de1, s12
	s_max_i32 s4, s4, 0
	s_and_b32 s76, s4, 0x7fffffc0
	s_lshl_b64 s[4:5], s[76:77], 8
	v_writelane_b32 v252, s4, 45
	v_readlane_b32 s40, v251, 20
	v_readlane_b32 s41, v251, 21
	v_writelane_b32 v252, s5, 46
	s_add_u32 s4, s20, 0x800000
	s_addc_u32 s5, s21, 0
	v_writelane_b32 v252, s4, 47
	v_readlane_b32 s46, v251, 26
	v_readlane_b32 s47, v251, 27
	v_writelane_b32 v252, s5, 48
	s_mov_b64 s[4:5], s[52:53]
	v_readlane_b32 s52, v251, 32
	v_readlane_b32 s64, v251, 44
	v_readlane_b32 s65, v251, 45
	s_mov_b64 s[24:25], s[64:65]
	s_mov_b64 s[64:65], s[4:5]
	s_add_u32 s4, s24, 0x800000
	s_addc_u32 s5, s25, 0
	v_writelane_b32 v252, s4, 49
	v_readlane_b32 s67, v251, 47
	s_mov_b32 s67, s14
	v_writelane_b32 v252, s5, 50
	s_add_u32 s4, s42, 0x8000
	s_addc_u32 s5, s43, 0
	s_lshl_b32 s90, s97, 3
	v_writelane_b32 v252, s4, 51
	s_cmpk_lt_i32 s95, 0x400
	v_readlane_b32 s56, v251, 36
	v_writelane_b32 v252, s5, 52
	s_cselect_b64 s[4:5], -1, 0
	v_writelane_b32 v252, s4, 53
	v_readlane_b32 s57, v251, 37
	v_readlane_b32 s58, v251, 38
	v_writelane_b32 v252, s5, 54
	s_ashr_i32 s4, s95, 4
	s_lshl_b32 s5, s95, 1
	s_and_b32 s4, s4, -16
	s_and_b32 s5, s5, 12
	s_or_b32 s4, s4, s5
	s_bfe_u32 s5, s95, 0x20006
	s_or_b32 s20, s4, s5
	s_and_b32 s4, s19, 8
	s_or_b32 s23, s4, s8
	s_mov_b64 s[4:5], 0
	v_writelane_b32 v252, s4, 55
	s_cmp_lg_u64 s[50:51], 0
	v_readlane_b32 s59, v251, 39
	v_writelane_b32 v252, s5, 56
	s_cselect_b64 s[4:5], -1, 0
	v_writelane_b32 v252, s4, 57
	s_cmp_gt_i32 s65, 3
	v_readlane_b32 s48, v251, 28
	v_writelane_b32 v252, s5, 58
	s_cselect_b64 s[4:5], -1, 0
	v_writelane_b32 v252, s4, 59
	s_cmpk_gt_i32 s97, 0xff
	v_readlane_b32 s49, v251, 29
	v_writelane_b32 v252, s5, 60
	s_cselect_b64 s[4:5], -1, 0
	v_writelane_b32 v252, s4, 61
	s_cmpk_lt_i32 s95, 0x80
	v_readlane_b32 s53, v251, 33
	v_writelane_b32 v252, s5, 62
	s_cselect_b64 s[4:5], -1, 0
	s_lshl_b32 s14, s1, 4
	v_writelane_b32 v252, s4, 63
	s_cmpk_lt_u32 s95, 0x100
	v_readlane_b32 s54, v251, 34
	v_writelane_b32 v253, s5, 0
	s_cselect_b64 s[4:5], -1, 0
	v_writelane_b32 v253, s4, 1
	s_lshr_b32 s11, s95, 5
	s_or_b32 s12, s7, s11
	v_writelane_b32 v253, s5, 2
	s_bfe_u32 s4, s95, 0x10003
	s_lshl_b32 s13, s12, 21
	s_lshl_b32 s25, s4, 20
	s_lshl_b32 s12, s12, 8
	s_lshl_b32 s4, s4, 7
	s_bfe_u32 s5, s95, 0x10004
	v_writelane_b32 v253, s13, 3
	s_or_b32 s4, s12, s4
	s_lshl_b32 s24, s5, 21
	v_writelane_b32 v253, s4, 4
	s_lshl_b32 s4, s5, 8
	s_cmpk_gt_i32 s95, 0x7f
	v_writelane_b32 v253, s4, 5
	s_cselect_b64 s[4:5], -1, 0
	v_writelane_b32 v253, s4, 6
	v_readlane_b32 s55, v251, 35
	v_readlane_b32 s60, v251, 40
	v_writelane_b32 v253, s5, 7
	s_add_i32 s5, s95, 0xffffff80
	s_cmp_lt_u32 s5, 16
	s_cselect_b64 s[12:13], -1, 0
	s_add_i32 s4, s95, 0x78
	v_writelane_b32 v253, s12, 8
	s_cmp_lt_u32 s5, 8
	v_readlane_b32 s61, v251, 41
	v_writelane_b32 v253, s13, 9
	s_cselect_b32 s12, s95, s4
	s_cmp_gt_u32 s5, 7
	v_writelane_b32 v253, s5, 10
	s_cselect_b64 s[4:5], -1, 0
	s_and_b32 s15, s12, 0x7f
	s_and_b64 s[12:13], s[4:5], exec
	s_cselect_b32 s12, 0x200000, 0
	v_writelane_b32 v253, s12, 11
	v_writelane_b32 v253, s15, 12
	s_lshl_b32 s12, s15, 21
	v_writelane_b32 v253, s12, 13
	s_add_i32 s12, s18, 0xfffec000
	s_cmpk_gt_i32 s95, 0x8f
	v_writelane_b32 v253, s12, 14
	s_cselect_b64 s[12:13], -1, 0
	s_and_b64 s[2:3], s[12:13], s[2:3]
	v_writelane_b32 v253, s2, 15
	v_cndmask_b32_e64 v226, 0, 1, s[4:5]
	s_movk_i32 s4, 0xe1
	v_writelane_b32 v253, s3, 16
	s_add_i32 s2, s22, 0xfffffb80
	s_cmpk_lt_i32 s2, 0x5600
	s_cselect_b64 s[2:3], -1, 0
	v_writelane_b32 v253, s2, 17
	s_cmp_lg_u64 s[44:45], 0
	s_mul_i32 s12, s1, 17
	v_writelane_b32 v253, s3, 18
	s_cselect_b64 s[2:3], -1, 0
	v_writelane_b32 v253, s2, 19
	s_cmpk_lt_i32 s95, 0x100
	v_readlane_b32 s62, v251, 42
	v_writelane_b32 v253, s3, 20
	s_cselect_b64 s[2:3], -1, 0
	v_writelane_b32 v253, s2, 21
	s_cmpk_lt_i32 s95, 0x1580
	v_readlane_b32 s63, v251, 43
	v_writelane_b32 v253, s3, 22
	s_cselect_b64 s[2:3], -1, 0
	v_writelane_b32 v253, s2, 23
	s_cmpk_lt_i32 s28, 0x2b00
	v_readlane_b32 s66, v251, 46
	v_writelane_b32 v253, s3, 24
	s_cselect_b64 s[2:3], -1, 0
	v_writelane_b32 v253, s2, 25
	s_cmp_lt_i32 s1, 0
	s_cselect_b32 s4, s4, 0xe0
	v_writelane_b32 v253, s3, 26
	v_cmp_eq_u32_e64 s[2:3], 0, v0
	s_mul_i32 s4, s1, s4
	v_mov_b32_e32 v145, 0
	v_writelane_b32 v253, s2, 27
	s_mov_b64 s[88:89], 0x80
	s_movk_i32 s60, 0xf000
	v_writelane_b32 v253, s3, 28
	s_mul_i32 s2, s1, 9
	s_mul_i32 s3, s1, 5
	s_cselect_b32 s5, s2, s9
	s_movk_i32 s2, 0x2b1
	s_cselect_b32 s3, s3, s10
	s_cselect_b32 s9, s12, s14
	s_cselect_b32 s14, s2, 0x2b0
	s_add_i32 s4, s4, s0
	s_mul_hi_i32 s2, s4, 0x92492493
	s_add_i32 s2, s2, s4
	s_lshr_b32 s10, s2, 31
	s_ashr_i32 s2, s2, 7
	s_add_i32 s2, s2, s10
	s_mul_i32 s10, s2, 0xe0
	s_sub_i32 s4, s4, s10
	s_lshl_b32 s12, s2, 3
	s_bfe_u32 s2, s4, 0x3001c
	s_add_i32 s10, s4, s2
	s_sext_i32_i16 s13, s10
	s_and_b32 s10, s10, 0xfff8
	s_sub_i32 s4, s4, s10
	s_sext_i32_i16 s4, s4
	s_add_i32 s26, s12, s4
	s_ashr_i32 s4, s13, 3
	v_writelane_b32 v253, s4, 29
	s_add_i32 s4, s5, s0
	s_ashr_i32 s5, s4, 31
	s_lshr_b32 s5, s5, 27
	s_add_i32 s5, s4, s5
	s_ashr_i32 s10, s5, 5
	s_and_b32 s5, s5, 0xffe0
	s_sub_i32 s5, s4, s5
	s_bfe_i32 s4, s5, 0x80000
	s_lshr_b32 s12, s4, 7
	s_bfe_u32 s4, s12, 0x30005
	s_lshr_b32 s2, s13, 3
	s_add_i32 s13, s5, s4
	s_bfe_i32 s4, s13, 0x80000
	s_and_b32 s13, s13, 0xf8
	s_sub_i32 s13, s5, s13
	s_lshl_b32 s10, s10, 3
	s_sext_i32_i16 s15, s4
	s_sext_i32_i8 s13, s13
	s_add_i32 s30, s10, s13
	s_ashr_i32 s10, s15, 3
	v_writelane_b32 v253, s10, 30
	s_bfe_u32 s10, s12, 0x40004
	s_add_i32 s5, s5, s10
	s_bfe_i32 s5, s5, 0x80000
	s_sext_i32_i16 s5, s5
	s_lshr_b32 s10, s5, 4
	s_bfe_i64 s[12:13], s[10:11], 0x100000
	s_mov_b32 s10, s30
	s_ashr_i32 s31, s30, 31
	v_writelane_b32 v253, s10, 31
	s_lshr_b32 s4, s15, 3
	s_lshl_b64 s[30:31], s[30:31], 20
	v_writelane_b32 v253, s11, 32
	v_writelane_b32 v253, s30, 33
	s_bfe_i64 s[4:5], s[4:5], 0x100000
	s_lshl_b64 s[4:5], s[4:5], 21
	v_writelane_b32 v253, s31, 34
	v_writelane_b32 v253, s4, 35
	s_add_i32 s3, s3, s0
	s_ashr_i32 s21, s20, 31
	v_writelane_b32 v253, s5, 36
	s_lshl_b64 s[4:5], s[12:13], 24
	v_writelane_b32 v253, s4, 37
	s_mul_i32 s1, s1, s14
	s_add_i32 s1, s1, s0
	v_writelane_b32 v253, s5, 38
	s_or_b32 s4, s7, s8
	v_writelane_b32 v253, s4, 39
	s_lshl_b32 s4, s4, 21
	v_writelane_b32 v253, s4, 40
	s_ashr_i32 s4, s3, 31
	s_lshr_b32 s4, s4, 28
	s_add_i32 s4, s3, s4
	s_ashr_i32 s5, s4, 4
	s_and_b32 s4, s4, 0xfff0
	s_sub_i32 s3, s3, s4
	s_bfe_i32 s4, s3, 0x80000
	s_bfe_u32 s4, s4, 0x3000c
	s_add_i32 s7, s3, s4
	s_bfe_i32 s4, s7, 0x80000
	s_and_b32 s7, s7, 0xf8
	s_sub_i32 s3, s3, s7
	s_lshl_b32 s5, s5, 3
	s_sext_i32_i16 s8, s4
	s_sext_i32_i8 s3, s3
	s_add_i32 s12, s5, s3
	s_ashr_i32 s3, s8, 3
	s_lshr_b32 s4, s8, 3
	v_writelane_b32 v253, s3, 41
	s_mov_b32 s8, s12
	s_ashr_i32 s13, s12, 31
	v_writelane_b32 v253, s8, 42
	s_lshl_b64 s[12:13], s[12:13], 18
	s_bfe_i64 s[4:5], s[4:5], 0x100000
	v_writelane_b32 v253, s9, 43
	v_writelane_b32 v253, s12, 44
	s_lshl_b32 s3, s23, 21
	s_ashr_i32 s27, s26, 31
	v_writelane_b32 v253, s13, 45
	s_lshl_b64 s[12:13], s[4:5], 18
	v_writelane_b32 v253, s12, 46
	s_lshl_b64 s[4:5], s[4:5], 22
	v_mov_b32_e32 v227, 1
	v_writelane_b32 v253, s13, 47
	v_writelane_b32 v253, s4, 48
	s_movk_i32 s86, 0x70
	s_movk_i32 s82, 0xfdff
	v_writelane_b32 v253, s5, 49
	s_lshl_b64 s[4:5], s[20:21], 21
	v_writelane_b32 v253, s4, 50
	s_mov_b32 s78, 0x3e0293ee
	s_mov_b32 s83, 0x41380000
	v_writelane_b32 v253, s5, 51
	v_writelane_b32 v253, s3, 52
	s_lshl_b32 s3, s23, 9
	s_and_b32 s3, s3, 0x1800
	v_writelane_b32 v253, s3, 53
	s_lshl_b32 s3, s23, 19
	v_writelane_b32 v253, s3, 54
	s_add_i32 s3, s9, s0
	s_ashr_i32 s4, s3, 31
	s_lshr_b32 s4, s4, 28
	s_add_i32 s4, s3, s4
	s_ashr_i32 s5, s4, 4
	s_and_b32 s4, s4, 0xfff0
	s_sub_i32 s3, s3, s4
	s_bfe_i32 s4, s3, 0x80000
	s_bfe_u32 s4, s4, 0x3000c
	s_add_i32 s7, s3, s4
	s_bfe_i32 s4, s7, 0x80000
	s_and_b32 s7, s7, 0xf8
	s_sub_i32 s3, s3, s7
	s_lshl_b32 s5, s5, 3
	s_sext_i32_i16 s8, s4
	s_sext_i32_i8 s3, s3
	s_add_i32 s12, s5, s3
	s_ashr_i32 s3, s8, 3
	s_lshr_b32 s4, s8, 3
	v_writelane_b32 v253, s3, 55
	s_mov_b32 s8, s12
	s_ashr_i32 s13, s12, 31
	v_writelane_b32 v253, s8, 56
	s_bfe_i64 s[4:5], s[4:5], 0x100000
	s_lshl_b64 s[4:5], s[4:5], 21
	v_writelane_b32 v253, s9, 57
	s_lshl_b64 s[8:9], s[12:13], 21
	v_writelane_b32 v253, s8, 58
	s_lshl_b32 s3, s23, 18
	s_mul_hi_i32 s0, s1, 0x2fa0be83
	v_writelane_b32 v253, s9, 59
	v_writelane_b32 v253, s4, 60
	s_movk_i32 s61, 0xe000
	s_brev_b32 s63, -2
	v_writelane_b32 v253, s5, 61
	s_mov_b32 s4, s20
	v_writelane_b32 v253, s4, 62
	s_brev_b32 s68, 1
	v_mov_b32_e32 v228, 0x358637bd
	v_writelane_b32 v253, s5, 63
	s_lshl_b64 s[4:5], s[20:21], 18
	v_writelane_b32 v254, s4, 0
	s_mov_b32 s38, 0xf800000
	v_mov_b32_e32 v229, 0x260
	v_writelane_b32 v254, s5, 1
	v_writelane_b32 v254, s23, 2
	v_writelane_b32 v254, s3, 3
	s_lshr_b32 s3, s0, 31
	s_ashr_i32 s0, s0, 7
	s_add_i32 s0, s0, s3
	s_lshl_b32 s3, s0, 3
	s_mulk_i32 s0, 0x2b0
	s_sub_i32 s1, s1, s0
	s_bfe_u32 s0, s1, 0x3001c
	s_add_i32 s4, s1, s0
	s_sext_i32_i16 s5, s4
	s_and_b32 s4, s4, 0xfff8
	s_sub_i32 s1, s1, s4
	s_sext_i32_i16 s1, s1
	s_add_i32 s8, s3, s1
	s_ashr_i32 s1, s5, 3
	v_writelane_b32 v254, s1, 4
	s_mov_b32 s4, s26
	s_lshr_b32 s0, s5, 3
	v_writelane_b32 v254, s4, 5
	s_bfe_i64 s[2:3], s[2:3], 0x100000
	s_lshl_b64 s[2:3], s[2:3], 21
	v_writelane_b32 v254, s5, 6
	s_lshl_b64 s[4:5], s[26:27], 21
	v_writelane_b32 v254, s4, 7
	s_ashr_i32 s9, s8, 31
	s_bfe_i64 s[0:1], s[0:1], 0x100000
	v_writelane_b32 v254, s5, 8
	v_writelane_b32 v254, s2, 9
	s_lshl_b64 s[0:1], s[0:1], 21
	s_mov_b64 s[4:5], -1
	v_writelane_b32 v254, s3, 10
	s_mov_b32 s2, s8
	v_writelane_b32 v254, s2, 11
	s_mov_b32 s39, 0xf7fff000
	s_brev_b32 s40, 31
	v_writelane_b32 v254, s3, 12
	s_lshl_b64 s[2:3], s[8:9], 21
	v_writelane_b32 v254, s2, 13
	s_add_u32 s74, s16, 0x4400
	s_addc_u32 s75, s17, 0
	v_writelane_b32 v254, s3, 14
	v_writelane_b32 v254, s0, 15
	s_ashr_i32 s91, s90, 31
	s_lshl_b64 s[56:57], s[90:91], 13
	v_writelane_b32 v254, s1, 16
	v_writelane_b32 v254, s28, 17
	s_lshl_b32 s0, s28, 6
	v_writelane_b32 v254, s0, 18
	s_lshl_b32 s1, s97, 9
	s_lshl_b32 s0, s6, 9
	s_sub_i32 s0, s1, s0
	v_writelane_b32 v254, s0, 19
	v_writelane_b32 v254, s19, 20
	s_ashr_i32 s0, s19, 31
	v_writelane_b32 v252, s1, 3
	v_writelane_b32 v254, s0, 21
	s_lshl_b64 s[0:1], s[90:91], 2
	v_writelane_b32 v252, s0, 1
	s_lshl_b64 s[58:59], s[90:91], 8
	s_movk_i32 s41, 0xd000
	v_writelane_b32 v252, s1, 2
	s_add_u32 s0, s36, 0x3810
	v_writelane_b32 v254, s0, 22
	s_addc_u32 s0, s37, 0
	v_writelane_b32 v254, s0, 23
	s_lshl_b64 s[0:1], s[90:91], 14
	v_writelane_b32 v254, s0, 24
	v_writelane_b32 v252, s56, 7
	v_mov_b32_e32 v230, 0xff800000
	v_writelane_b32 v254, s1, 25
	v_writelane_b32 v254, s24, 26
	s_or_b32 s0, s24, 0x7000100
	v_writelane_b32 v254, s0, 27
	s_and_b32 s0, s95, 7
	s_lshl_b32 s0, s0, 24
	s_lshl_b32 s1, s11, 21
	s_add_i32 s0, s0, s1
	v_writelane_b32 v254, s25, 28
	s_or_b32 s0, s25, s0
	v_writelane_b32 v254, s0, 29
	s_add_u32 s0, s0, 0x29000080
	v_writelane_b32 v254, s0, 30
	s_addc_u32 s0, 0, 0
	v_writelane_b32 v254, s0, 31
	v_writelane_b32 v254, s22, 32
	s_add_i32 s0, s22, 0xfffff800
	v_writelane_b32 v254, s0, 33
	s_add_i32 s0, s18, 0xfffee000
	v_writelane_b32 v254, s0, 34
	v_readlane_b32 s0, v251, 4
	v_readlane_b32 s2, v251, 6
	v_readlane_b32 s1, v251, 5
	v_readlane_b32 s3, v251, 7
	s_add_u32 s0, s2, 0x3810
	v_writelane_b32 v251, s81, 57
	v_writelane_b32 v254, s0, 35
	s_addc_u32 s0, s3, 0
	v_writelane_b32 v251, s67, 56
	v_writelane_b32 v254, s0, 36
	s_add_i32 s2, 0, 0x18400
	v_writelane_b32 v251, s58, 61
	s_movk_i32 s0, 0x5600
	s_mov_b32 s1, 0x15800
	v_writelane_b32 v254, s2, 37
	v_mov_b32_e32 v231, 0x49742401
	v_mov_b64_e32 v[184:185], 0x400
	v_mov_b64_e32 v[186:187], 0x3ff
	v_mov_b64_e32 v[192:193], 0x1580
	v_mov_b64_e32 v[194:195], 0x157f
	s_mov_b32 s44, s77
	v_writelane_b32 v252, s57, 8
	v_writelane_b32 v251, s59, 62
	s_branch .LBB0_684

.LBB0_869:
	v_readlane_b32 s8, v251, 48
	v_readlane_b32 s9, v251, 54
	v_readlane_b32 s2, v251, 10
	v_readlane_b32 s3, v251, 11
	v_readlane_b32 s4, v251, 24
	v_readlane_b32 s5, v251, 25
	v_readlane_b32 s6, v251, 2
	v_readlane_b32 s7, v251, 3
	s_nop 0
	s_sub_i32 s8, s8, 128
	s_lshl_b32 s8, s8, 3
	s_lshr_b32 s9, s9, 6
	s_add_i32 s8, s8, s9
	s_mul_i32 s32, s9, 0x2100
	s_add_u32 s2, s2, 0x15800000
	s_addc_u32 s3, s3, 0
	s_add_u32 s4, s4, 0x8000
	s_addc_u32 s5, s5, 0
	s_add_u32 s6, s6, 0x13800000
	s_addc_u32 s7, s7, 0
	v_mbcnt_lo_u32_b32 v32, -1, 0
	v_mbcnt_hi_u32_b32 v32, -1, v32
	v_lshrrev_b32_e32 v34, 4, v32
	v_and_b32_e32 v35, 15, v32
	v_and_b32_e32 v36, 7, v32
	v_lshrrev_b32_e32 v37, 3, v32
	v_lshlrev_b32_e32 v30, 3, v34
	v_mul_u32_u24_e32 v38, 0x2b000, v34
	v_lshl_add_u32 v38, v35, 4, v38
	v_mov_b32_e32 v0, v38
	v_add_u32_e32 v1, 0x15800, v38
	v_add_u32_e32 v2, 0xac000, v38
	v_add_u32_e32 v3, 0xc1800, v38
	v_add_u32_e32 v4, 0x158000, v38
	v_add_u32_e32 v5, 0x16d800, v38
	v_add_u32_e32 v6, 0x204000, v38
	v_add_u32_e32 v7, 0x219800, v38
	v_add_u32_e32 v8, 0x2b0000, v38
	v_add_u32_e32 v9, 0x2c5800, v38
	v_add_u32_e32 v10, 0x35c000, v38
	v_add_u32_e32 v11, 0x371800, v38
	v_add_u32_e32 v16, 0x408000, v38
	v_add_u32_e32 v17, 0x41d800, v38
	v_add_u32_e32 v18, 0x4b4000, v38
	v_add_u32_e32 v19, 0x4c9800, v38
	v_lshlrev_b32_e32 v39, 13, v37
	v_lshl_add_u32 v39, v36, 4, v39
	v_mov_b32_e32 v20, v39
	v_add_u32_e32 v21, 0x10000, v39
	v_add_u32_e32 v22, 0x20000, v39
	v_add_u32_e32 v23, 0x30000, v39
	v_add_u32_e32 v24, 0x40000, v39
	v_add_u32_e32 v25, 0x50000, v39
	v_add_u32_e32 v26, 0x60000, v39
	v_add_u32_e32 v27, 0x70000, v39
	v_mul_u32_u24_e32 v28, 0x104, v34
	v_lshl_add_u32 v28, v35, 4, v28
	v_add_u32_e32 v28, s32, v28
	v_mul_u32_u24_e32 v29, 0x410, v36
	v_lshl_add_u32 v29, v37, 2, v29
	v_add_u32_e32 v29, s32, v29
	s_cmpk_lt_i32 s8, 0x5600
	s_cbranch_scc0 .Ltrl_done
	s_mul_hi_u32 s23, s8, 0x2fa0be83
	s_lshr_b32 s23, s23, 6
	s_mul_i32 s25, s23, 0x158
	s_sub_i32 s24, s8, s25
	s_mul_i32 s25, s23, 0x560000
	s_lshl_b32 s33, s24, 8
	s_add_i32 s25, s25, s33
	s_add_u32 s26, s2, s25
	s_addc_u32 s27, s3, 0
	s_lshl_b32 s25, s23, 8
	s_add_u32 s28, s4, s25
	s_addc_u32 s29, s5, 0
	global_load_dwordx4 v[44:47], v0, s[26:27]
	global_load_dwordx4 v[48:51], v1, s[26:27]
	global_load_dwordx4 v[52:55], v2, s[26:27]
	global_load_dwordx4 v[56:59], v3, s[26:27]
	global_load_dwordx4 v[60:63], v4, s[26:27]
	global_load_dwordx4 v[64:67], v5, s[26:27]
	global_load_dwordx4 v[68:71], v6, s[26:27]
	global_load_dwordx4 v[72:75], v7, s[26:27]
	global_load_dwordx4 v[76:79], v8, s[26:27]
	global_load_dwordx4 v[80:83], v9, s[26:27]
	global_load_dwordx4 v[84:87], v10, s[26:27]
	global_load_dwordx4 v[88:91], v11, s[26:27]
	global_load_dwordx4 v[92:95], v16, s[26:27]
	global_load_dwordx4 v[104:107], v17, s[26:27]
	global_load_dwordx4 v[108:111], v18, s[26:27]
	global_load_dwordx4 v[112:115], v19, s[26:27]
	global_load_dwordx2 v[116:117], v30, s[28:29]
	global_load_dwordx2 v[118:119], v30, s[28:29] offset:32
	global_load_dwordx2 v[120:121], v30, s[28:29] offset:64
	global_load_dwordx2 v[122:123], v30, s[28:29] offset:96
	global_load_dwordx2 v[124:125], v30, s[28:29] offset:128
	global_load_dwordx2 v[126:127], v30, s[28:29] offset:160
	global_load_dwordx2 v[128:129], v30, s[28:29] offset:192
	global_load_dwordx2 v[130:131], v30, s[28:29] offset:224
	s_waitcnt vmcnt(0)
	s_branch .Ltrl_body
.Ltrl_loop:
	s_waitcnt vmcnt(8)
.Ltrl_body:
	s_mul_hi_u32 s23, s8, 0x2fa0be83
	s_lshr_b32 s23, s23, 6
	s_mul_i32 s25, s23, 0x158
	s_sub_i32 s24, s8, s25
	s_cmpk_ge_u32 s24, 0xac
	s_cselect_b32 s25, 0xac, 0
	s_cselect_b32 s33, 0x80, 0
	s_sub_i32 s24, s24, s25
	s_and_b32 s25, s24, 1
	s_lshl_b32 s25, s25, 6
	s_lshr_b32 s24, s24, 1
	s_lshl_b32 s24, s24, 8
	s_add_i32 s24, s24, s25
	s_add_i32 s24, s24, s33
	s_lshl_b32 s24, s24, 13
	s_lshl_b32 s25, s23, 7
	s_add_i32 s24, s24, s25
	s_add_u32 s30, s6, s24
	s_addc_u32 s31, s7, 0
	v_mul_f32_e32 v34, v44, v116
	v_mul_f32_e32 v35, v48, v117
	v_cvt_pk_bf16_f32 v38, v34, v35
	ds_write_b32 v28, v38
	v_mul_f32_e32 v36, v45, v116
	v_mul_f32_e32 v37, v49, v117
	v_cvt_pk_bf16_f32 v39, v36, v37
	ds_write_b32 v28, v39 offset:4
	v_mul_f32_e32 v34, v46, v116
	v_mul_f32_e32 v35, v50, v117
	v_cvt_pk_bf16_f32 v40, v34, v35
	ds_write_b32 v28, v40 offset:8
	v_mul_f32_e32 v36, v47, v116
	v_mul_f32_e32 v37, v51, v117
	v_cvt_pk_bf16_f32 v41, v36, v37
	ds_write_b32 v28, v41 offset:12
	v_mul_f32_e32 v34, v52, v118
	v_mul_f32_e32 v35, v56, v119
	v_cvt_pk_bf16_f32 v38, v34, v35
	ds_write_b32 v28, v38 offset:1040
	v_mul_f32_e32 v36, v53, v118
	v_mul_f32_e32 v37, v57, v119
	v_cvt_pk_bf16_f32 v39, v36, v37
	ds_write_b32 v28, v39 offset:1044
	v_mul_f32_e32 v34, v54, v118
	v_mul_f32_e32 v35, v58, v119
	v_cvt_pk_bf16_f32 v40, v34, v35
	ds_write_b32 v28, v40 offset:1048
	v_mul_f32_e32 v36, v55, v118
	v_mul_f32_e32 v37, v59, v119
	v_cvt_pk_bf16_f32 v41, v36, v37
	ds_write_b32 v28, v41 offset:1052
	v_mul_f32_e32 v34, v60, v120
	v_mul_f32_e32 v35, v64, v121
	v_cvt_pk_bf16_f32 v38, v34, v35
	ds_write_b32 v28, v38 offset:2080
	v_mul_f32_e32 v36, v61, v120
	v_mul_f32_e32 v37, v65, v121
	v_cvt_pk_bf16_f32 v39, v36, v37
	ds_write_b32 v28, v39 offset:2084
	v_mul_f32_e32 v34, v62, v120
	v_mul_f32_e32 v35, v66, v121
	v_cvt_pk_bf16_f32 v40, v34, v35
	ds_write_b32 v28, v40 offset:2088
	v_mul_f32_e32 v36, v63, v120
	v_mul_f32_e32 v37, v67, v121
	v_cvt_pk_bf16_f32 v41, v36, v37
	ds_write_b32 v28, v41 offset:2092
	v_mul_f32_e32 v34, v68, v122
	v_mul_f32_e32 v35, v72, v123
	v_cvt_pk_bf16_f32 v38, v34, v35
	ds_write_b32 v28, v38 offset:3120
	v_mul_f32_e32 v36, v69, v122
	v_mul_f32_e32 v37, v73, v123
	v_cvt_pk_bf16_f32 v39, v36, v37
	ds_write_b32 v28, v39 offset:3124
	v_mul_f32_e32 v34, v70, v122
	v_mul_f32_e32 v35, v74, v123
	v_cvt_pk_bf16_f32 v40, v34, v35
	ds_write_b32 v28, v40 offset:3128
	v_mul_f32_e32 v36, v71, v122
	v_mul_f32_e32 v37, v75, v123
	v_cvt_pk_bf16_f32 v41, v36, v37
	ds_write_b32 v28, v41 offset:3132
	v_mul_f32_e32 v34, v76, v124
	v_mul_f32_e32 v35, v80, v125
	v_cvt_pk_bf16_f32 v38, v34, v35
	ds_write_b32 v28, v38 offset:4160
	v_mul_f32_e32 v36, v77, v124
	v_mul_f32_e32 v37, v81, v125
	v_cvt_pk_bf16_f32 v39, v36, v37
	ds_write_b32 v28, v39 offset:4164
	v_mul_f32_e32 v34, v78, v124
	v_mul_f32_e32 v35, v82, v125
	v_cvt_pk_bf16_f32 v40, v34, v35
	ds_write_b32 v28, v40 offset:4168
	v_mul_f32_e32 v36, v79, v124
	v_mul_f32_e32 v37, v83, v125
	v_cvt_pk_bf16_f32 v41, v36, v37
	ds_write_b32 v28, v41 offset:4172
	v_mul_f32_e32 v34, v84, v126
	v_mul_f32_e32 v35, v88, v127
	v_cvt_pk_bf16_f32 v38, v34, v35
	ds_write_b32 v28, v38 offset:5200
	v_mul_f32_e32 v36, v85, v126
	v_mul_f32_e32 v37, v89, v127
	v_cvt_pk_bf16_f32 v39, v36, v37
	ds_write_b32 v28, v39 offset:5204
	v_mul_f32_e32 v34, v86, v126
	v_mul_f32_e32 v35, v90, v127
	v_cvt_pk_bf16_f32 v40, v34, v35
	ds_write_b32 v28, v40 offset:5208
	v_mul_f32_e32 v36, v87, v126
	v_mul_f32_e32 v37, v91, v127
	v_cvt_pk_bf16_f32 v41, v36, v37
	ds_write_b32 v28, v41 offset:5212
	v_mul_f32_e32 v34, v92, v128
	v_mul_f32_e32 v35, v104, v129
	v_cvt_pk_bf16_f32 v38, v34, v35
	ds_write_b32 v28, v38 offset:6240
	v_mul_f32_e32 v36, v93, v128
	v_mul_f32_e32 v37, v105, v129
	v_cvt_pk_bf16_f32 v39, v36, v37
	ds_write_b32 v28, v39 offset:6244
	v_mul_f32_e32 v34, v94, v128
	v_mul_f32_e32 v35, v106, v129
	v_cvt_pk_bf16_f32 v40, v34, v35
	ds_write_b32 v28, v40 offset:6248
	v_mul_f32_e32 v36, v95, v128
	v_mul_f32_e32 v37, v107, v129
	v_cvt_pk_bf16_f32 v41, v36, v37
	ds_write_b32 v28, v41 offset:6252
	v_mul_f32_e32 v34, v108, v130
	v_mul_f32_e32 v35, v112, v131
	v_cvt_pk_bf16_f32 v38, v34, v35
	ds_write_b32 v28, v38 offset:7280
	v_mul_f32_e32 v36, v109, v130
	v_mul_f32_e32 v37, v113, v131
	v_cvt_pk_bf16_f32 v39, v36, v37
	ds_write_b32 v28, v39 offset:7284
	v_mul_f32_e32 v34, v110, v130
	v_mul_f32_e32 v35, v114, v131
	v_cvt_pk_bf16_f32 v40, v34, v35
	ds_write_b32 v28, v40 offset:7288
	v_mul_f32_e32 v36, v111, v130
	v_mul_f32_e32 v37, v115, v131
	v_cvt_pk_bf16_f32 v41, v36, v37
	ds_write_b32 v28, v41 offset:7292
	s_add_i32 s9, s8, 0x400
	s_cmpk_lt_i32 s9, 0x5600
	s_cbranch_scc0 .Ltrl_noload
	s_mul_hi_u32 s23, s9, 0x2fa0be83
	s_lshr_b32 s23, s23, 6
	s_mul_i32 s25, s23, 0x158
	s_sub_i32 s24, s9, s25
	s_mul_i32 s25, s23, 0x560000
	s_lshl_b32 s33, s24, 8
	s_add_i32 s25, s25, s33
	s_add_u32 s26, s2, s25
	s_addc_u32 s27, s3, 0
	s_lshl_b32 s25, s23, 8
	s_add_u32 s28, s4, s25
	s_addc_u32 s29, s5, 0
	global_load_dwordx4 v[44:47], v0, s[26:27]
	global_load_dwordx4 v[48:51], v1, s[26:27]
	global_load_dwordx4 v[52:55], v2, s[26:27]
	global_load_dwordx4 v[56:59], v3, s[26:27]
	global_load_dwordx4 v[60:63], v4, s[26:27]
	global_load_dwordx4 v[64:67], v5, s[26:27]
	global_load_dwordx4 v[68:71], v6, s[26:27]
	global_load_dwordx4 v[72:75], v7, s[26:27]
	global_load_dwordx4 v[76:79], v8, s[26:27]
	global_load_dwordx4 v[80:83], v9, s[26:27]
	global_load_dwordx4 v[84:87], v10, s[26:27]
	global_load_dwordx4 v[88:91], v11, s[26:27]
	global_load_dwordx4 v[92:95], v16, s[26:27]
	global_load_dwordx4 v[104:107], v17, s[26:27]
	global_load_dwordx4 v[108:111], v18, s[26:27]
	global_load_dwordx4 v[112:115], v19, s[26:27]
	global_load_dwordx2 v[116:117], v30, s[28:29]
	global_load_dwordx2 v[118:119], v30, s[28:29] offset:32
	global_load_dwordx2 v[120:121], v30, s[28:29] offset:64
	global_load_dwordx2 v[122:123], v30, s[28:29] offset:96
	global_load_dwordx2 v[124:125], v30, s[28:29] offset:128
	global_load_dwordx2 v[126:127], v30, s[28:29] offset:160
	global_load_dwordx2 v[128:129], v30, s[28:29] offset:192
	global_load_dwordx2 v[130:131], v30, s[28:29] offset:224
.Ltrl_noload:
	s_waitcnt lgkmcnt(0)
	ds_read2_b32 v[180:181], v29 offset0:0 offset1:65
	ds_read2_b32 v[182:183], v29 offset0:130 offset1:195
	ds_read2_b32 v[188:189], v29 offset0:8 offset1:73
	ds_read2_b32 v[190:191], v29 offset0:138 offset1:203
	ds_read2_b32 v[196:197], v29 offset0:16 offset1:81
	ds_read2_b32 v[198:199], v29 offset0:146 offset1:211
	ds_read2_b32 v[200:201], v29 offset0:24 offset1:89
	ds_read2_b32 v[202:203], v29 offset0:154 offset1:219
	ds_read2_b32 v[204:205], v29 offset0:32 offset1:97
	ds_read2_b32 v[206:207], v29 offset0:162 offset1:227
	ds_read2_b32 v[232:233], v29 offset0:40 offset1:105
	ds_read2_b32 v[234:235], v29 offset0:170 offset1:235
	ds_read2_b32 v[236:237], v29 offset0:48 offset1:113
	ds_read2_b32 v[238:239], v29 offset0:178 offset1:243
	ds_read2_b32 v[240:241], v29 offset0:56 offset1:121
	ds_read2_b32 v[242:243], v29 offset0:186 offset1:251
	s_waitcnt lgkmcnt(0)
	global_store_dwordx4 v20, v[180:183], s[30:31]
	global_store_dwordx4 v21, v[188:191], s[30:31]
	global_store_dwordx4 v22, v[196:199], s[30:31]
	global_store_dwordx4 v23, v[200:203], s[30:31]
	global_store_dwordx4 v24, v[204:207], s[30:31]
	global_store_dwordx4 v25, v[232:235], s[30:31]
	global_store_dwordx4 v26, v[236:239], s[30:31]
	global_store_dwordx4 v27, v[240:243], s[30:31]
	s_mov_b32 s8, s9
	s_cmpk_lt_i32 s8, 0x5600
	s_cbranch_scc1 .Ltrl_loop
.Ltrl_done:
.LBB0_917:
	s_mul_i32 s2, s44, 14
	s_add_i32 s18, s2, 4
	s_cmp_ge_i32 s18, s65
	s_cbranch_scc1 .LBB0_966
	s_waitcnt vmcnt(0)
	s_waitcnt vmcnt(0) lgkmcnt(0)
	s_barrier
	s_mov_b64 s[2:3], exec
	v_readlane_b32 s4, v253, 27
	v_readlane_b32 s5, v253, 28
	s_and_b64 s[4:5], s[2:3], s[4:5]
	s_mov_b64 exec, s[4:5]
	s_cbranch_execz .LBB0_965
	v_mov_b32_e32 v0, s79
	s_waitcnt vmcnt(0) expcnt(0) lgkmcnt(0)
	ds_read_b32 v2, v0
	ds_read_b32 v0, v0 offset:4
	s_waitcnt lgkmcnt(1)
	v_cmp_ne_u32_e32 vcc, 0, v2
	s_cbranch_vccnz .LBB0_933
	v_readlane_b32 s6, v251, 0
	v_readlane_b32 s7, v251, 1
	s_load_dwordx2 s[4:5], s[6:7], 0x4
	s_mov_b32 s10, 0
	s_waitcnt lgkmcnt(0)
	s_mul_i32 s9, s4, s97
	s_mul_i32 s9, s9, s5
	s_branch .LBB0_922

.LBB0_1043:
	s_and_b64 vcc, exec, s[2:3]
	v_readlane_b32 s79, v254, 32
	s_add_i32 s79, s79, 0x2e00
	s_cbranch_vccnz .LBB0_1338
	v_readlane_b32 s2, v254, 49
	v_readlane_b32 s3, v254, 50
	s_add_u32 s26, s2, 0x8b200000
	s_addc_u32 s27, s3, 0
	s_add_u32 s4, s2, 0x8a400000
	s_addc_u32 s5, s3, 0
	v_writelane_b32 v254, s4, 52
	s_mov_b32 s97, 0
	s_nop 0
	v_writelane_b32 v254, s5, 53
	s_add_u32 s4, s2, 0x8b400000
	s_addc_u32 s5, s3, 0
	v_writelane_b32 v254, s4, 54
	s_nop 1
	v_writelane_b32 v254, s5, 55
	s_add_u32 s4, s2, 0x93400000
	v_writelane_b32 v254, s4, 56
	s_addc_u32 s4, s3, 0
	v_writelane_b32 v254, s4, 57
	s_add_u32 s4, s2, 0x8800000
	s_addc_u32 s5, s3, 0
	v_writelane_b32 v254, s4, 58
	s_nop 1
	v_writelane_b32 v254, s5, 59
	s_add_u32 s4, s2, 0x7000000
	s_addc_u32 s5, s3, 0
	v_writelane_b32 v254, s4, 60
	s_nop 1
	v_writelane_b32 v254, s5, 61
	s_add_u32 s4, s2, 0x4300000
	s_addc_u32 s5, s3, 0
	v_writelane_b32 v254, s4, 62
	s_nop 1
	v_writelane_b32 v254, s5, 63
	s_add_u32 s4, s2, 0x13800000
	s_addc_u32 s5, s3, 0
	v_writelane_b32 v250, s4, 0
	s_add_u32 s2, s2, 0x8b206000
	s_addc_u32 s3, s3, 0
	v_writelane_b32 v250, s5, 1
	v_writelane_b32 v250, s2, 2
	v_readlane_b32 s79, v254, 32
	s_add_i32 s79, s79, 0x2e00
	s_nop 0
	v_writelane_b32 v250, s3, 3
	v_writelane_b32 v250, s26, 4
	v_writelane_b32 v250, s27, 5

.LBB0_1803:
	v_readlane_b32 s8, v251, 48
	v_readlane_b32 s9, v251, 54
	v_readlane_b32 s2, v251, 10
	v_readlane_b32 s3, v251, 11
	v_readlane_b32 s4, v251, 24
	v_readlane_b32 s5, v251, 25
	v_readlane_b32 s6, v251, 2
	v_readlane_b32 s7, v251, 3
	s_nop 0
	s_sub_i32 s8, s8, 144
	s_lshl_b32 s8, s8, 3
	s_lshr_b32 s9, s9, 6
	s_add_i32 s8, s8, s9
	s_mul_i32 s32, s9, 0x2100
	s_add_u32 s6, s6, 0x8c00000
	s_addc_u32 s7, s7, 0
	v_mbcnt_lo_u32_b32 v32, -1, 0
	v_mbcnt_hi_u32_b32 v32, -1, v32
	v_lshrrev_b32_e32 v34, 4, v32
	v_and_b32_e32 v35, 15, v32
	v_and_b32_e32 v36, 7, v32
	v_lshrrev_b32_e32 v37, 3, v32
	v_lshlrev_b32_e32 v30, 3, v34
	v_mul_u32_u24_e32 v38, 0x2b000, v34
	v_lshl_add_u32 v38, v35, 4, v38
	v_mov_b32_e32 v0, v38
	v_add_u32_e32 v1, 0x15800, v38
	v_add_u32_e32 v2, 0xac000, v38
	v_add_u32_e32 v3, 0xc1800, v38
	v_add_u32_e32 v4, 0x158000, v38
	v_add_u32_e32 v5, 0x16d800, v38
	v_add_u32_e32 v6, 0x204000, v38
	v_add_u32_e32 v7, 0x219800, v38
	v_add_u32_e32 v8, 0x2b0000, v38
	v_add_u32_e32 v9, 0x2c5800, v38
	v_add_u32_e32 v10, 0x35c000, v38
	v_add_u32_e32 v11, 0x371800, v38
	v_add_u32_e32 v16, 0x408000, v38
	v_add_u32_e32 v17, 0x41d800, v38
	v_add_u32_e32 v18, 0x4b4000, v38
	v_add_u32_e32 v19, 0x4c9800, v38
	v_lshlrev_b32_e32 v39, 13, v37
	v_lshl_add_u32 v39, v36, 4, v39
	v_mov_b32_e32 v20, v39
	v_add_u32_e32 v21, 0x10000, v39
	v_add_u32_e32 v22, 0x20000, v39
	v_add_u32_e32 v23, 0x30000, v39
	v_add_u32_e32 v24, 0x40000, v39
	v_add_u32_e32 v25, 0x50000, v39
	v_add_u32_e32 v26, 0x60000, v39
	v_add_u32_e32 v27, 0x70000, v39
	v_mul_u32_u24_e32 v28, 0x104, v34
	v_lshl_add_u32 v28, v35, 4, v28
	v_add_u32_e32 v28, s32, v28
	v_mul_u32_u24_e32 v29, 0x410, v36
	v_lshl_add_u32 v29, v37, 2, v29
	v_add_u32_e32 v29, s32, v29
	s_cmpk_lt_i32 s8, 0x5600
	s_cbranch_scc0 .Ltrx_done
	s_mul_hi_u32 s23, s8, 0x2fa0be83
	s_lshr_b32 s23, s23, 6
	s_mul_i32 s25, s23, 0x158
	s_sub_i32 s24, s8, s25
	s_mul_i32 s25, s23, 0x560000
	s_lshl_b32 s33, s24, 8
	s_add_i32 s25, s25, s33
	s_add_u32 s26, s2, s25
	s_addc_u32 s27, s3, 0
	s_lshl_b32 s25, s23, 8
	s_add_u32 s28, s4, s25
	s_addc_u32 s29, s5, 0
	global_load_dwordx4 v[44:47], v0, s[26:27]
	global_load_dwordx4 v[48:51], v1, s[26:27]
	global_load_dwordx4 v[52:55], v2, s[26:27]
	global_load_dwordx4 v[56:59], v3, s[26:27]
	global_load_dwordx4 v[60:63], v4, s[26:27]
	global_load_dwordx4 v[64:67], v5, s[26:27]
	global_load_dwordx4 v[68:71], v6, s[26:27]
	global_load_dwordx4 v[72:75], v7, s[26:27]
	global_load_dwordx4 v[76:79], v8, s[26:27]
	global_load_dwordx4 v[80:83], v9, s[26:27]
	global_load_dwordx4 v[84:87], v10, s[26:27]
	global_load_dwordx4 v[88:91], v11, s[26:27]
	global_load_dwordx4 v[92:95], v16, s[26:27]
	global_load_dwordx4 v[104:107], v17, s[26:27]
	global_load_dwordx4 v[108:111], v18, s[26:27]
	global_load_dwordx4 v[112:115], v19, s[26:27]
	global_load_dwordx2 v[116:117], v30, s[28:29]
	global_load_dwordx2 v[118:119], v30, s[28:29] offset:32
	global_load_dwordx2 v[120:121], v30, s[28:29] offset:64
	global_load_dwordx2 v[122:123], v30, s[28:29] offset:96
	global_load_dwordx2 v[124:125], v30, s[28:29] offset:128
	global_load_dwordx2 v[126:127], v30, s[28:29] offset:160
	global_load_dwordx2 v[128:129], v30, s[28:29] offset:192
	global_load_dwordx2 v[130:131], v30, s[28:29] offset:224
	s_waitcnt vmcnt(0)
	s_branch .Ltrx_body

.Ltrx_body:
	s_mul_hi_u32 s23, s8, 0x2fa0be83
	s_lshr_b32 s23, s23, 6
	s_mul_i32 s25, s23, 0x158
	s_sub_i32 s24, s8, s25
	s_cmpk_ge_u32 s24, 0xac
	s_cselect_b32 s25, 0xac, 0
	s_cselect_b32 s33, 0x80, 0
	s_sub_i32 s24, s24, s25
	s_and_b32 s25, s24, 1
	s_lshl_b32 s25, s25, 6
	s_lshr_b32 s24, s24, 1
	s_lshl_b32 s24, s24, 8
	s_add_i32 s24, s24, s25
	s_add_i32 s24, s24, s33
	s_lshl_b32 s24, s24, 13
	s_lshl_b32 s25, s23, 7
	s_add_i32 s24, s24, s25
	s_add_u32 s30, s6, s24
	s_addc_u32 s31, s7, 0
	v_mul_f32_e32 v34, v44, v116
	v_mul_f32_e32 v35, v48, v117
	v_cvt_pk_bf16_f32 v38, v34, v35
	ds_write_b32 v28, v38
	v_mul_f32_e32 v36, v45, v116
	v_mul_f32_e32 v37, v49, v117
	v_cvt_pk_bf16_f32 v39, v36, v37
	ds_write_b32 v28, v39 offset:4
	v_mul_f32_e32 v34, v46, v116
	v_mul_f32_e32 v35, v50, v117
	v_cvt_pk_bf16_f32 v40, v34, v35
	ds_write_b32 v28, v40 offset:8
	v_mul_f32_e32 v36, v47, v116
	v_mul_f32_e32 v37, v51, v117
	v_cvt_pk_bf16_f32 v41, v36, v37
	ds_write_b32 v28, v41 offset:12
	v_mul_f32_e32 v34, v52, v118
	v_mul_f32_e32 v35, v56, v119
	v_cvt_pk_bf16_f32 v38, v34, v35
	ds_write_b32 v28, v38 offset:1040
	v_mul_f32_e32 v36, v53, v118
	v_mul_f32_e32 v37, v57, v119
	v_cvt_pk_bf16_f32 v39, v36, v37
	ds_write_b32 v28, v39 offset:1044
	v_mul_f32_e32 v34, v54, v118
	v_mul_f32_e32 v35, v58, v119
	v_cvt_pk_bf16_f32 v40, v34, v35
	ds_write_b32 v28, v40 offset:1048
	v_mul_f32_e32 v36, v55, v118
	v_mul_f32_e32 v37, v59, v119
	v_cvt_pk_bf16_f32 v41, v36, v37
	ds_write_b32 v28, v41 offset:1052
	v_mul_f32_e32 v34, v60, v120
	v_mul_f32_e32 v35, v64, v121
	v_cvt_pk_bf16_f32 v38, v34, v35
	ds_write_b32 v28, v38 offset:2080
	v_mul_f32_e32 v36, v61, v120
	v_mul_f32_e32 v37, v65, v121
	v_cvt_pk_bf16_f32 v39, v36, v37
	ds_write_b32 v28, v39 offset:2084
	v_mul_f32_e32 v34, v62, v120
	v_mul_f32_e32 v35, v66, v121
	v_cvt_pk_bf16_f32 v40, v34, v35
	ds_write_b32 v28, v40 offset:2088
	v_mul_f32_e32 v36, v63, v120
	v_mul_f32_e32 v37, v67, v121
	v_cvt_pk_bf16_f32 v41, v36, v37
	ds_write_b32 v28, v41 offset:2092
	v_mul_f32_e32 v34, v68, v122
	v_mul_f32_e32 v35, v72, v123
	v_cvt_pk_bf16_f32 v38, v34, v35
	ds_write_b32 v28, v38 offset:3120
	v_mul_f32_e32 v36, v69, v122
	v_mul_f32_e32 v37, v73, v123
	v_cvt_pk_bf16_f32 v39, v36, v37
	ds_write_b32 v28, v39 offset:3124
	v_mul_f32_e32 v34, v70, v122
	v_mul_f32_e32 v35, v74, v123
	v_cvt_pk_bf16_f32 v40, v34, v35
	ds_write_b32 v28, v40 offset:3128
	v_mul_f32_e32 v36, v71, v122
	v_mul_f32_e32 v37, v75, v123
	v_cvt_pk_bf16_f32 v41, v36, v37
	ds_write_b32 v28, v41 offset:3132
	v_mul_f32_e32 v34, v76, v124
	v_mul_f32_e32 v35, v80, v125
	v_cvt_pk_bf16_f32 v38, v34, v35
	ds_write_b32 v28, v38 offset:4160
	v_mul_f32_e32 v36, v77, v124
	v_mul_f32_e32 v37, v81, v125
	v_cvt_pk_bf16_f32 v39, v36, v37
	ds_write_b32 v28, v39 offset:4164
	v_mul_f32_e32 v34, v78, v124
	v_mul_f32_e32 v35, v82, v125
	v_cvt_pk_bf16_f32 v40, v34, v35
	ds_write_b32 v28, v40 offset:4168
	v_mul_f32_e32 v36, v79, v124
	v_mul_f32_e32 v37, v83, v125
	v_cvt_pk_bf16_f32 v41, v36, v37
	ds_write_b32 v28, v41 offset:4172
	v_mul_f32_e32 v34, v84, v126
	v_mul_f32_e32 v35, v88, v127
	v_cvt_pk_bf16_f32 v38, v34, v35
	ds_write_b32 v28, v38 offset:5200
	v_mul_f32_e32 v36, v85, v126
	v_mul_f32_e32 v37, v89, v127
	v_cvt_pk_bf16_f32 v39, v36, v37
	ds_write_b32 v28, v39 offset:5204
	v_mul_f32_e32 v34, v86, v126
	v_mul_f32_e32 v35, v90, v127
	v_cvt_pk_bf16_f32 v40, v34, v35
	ds_write_b32 v28, v40 offset:5208
	v_mul_f32_e32 v36, v87, v126
	v_mul_f32_e32 v37, v91, v127
	v_cvt_pk_bf16_f32 v41, v36, v37
	ds_write_b32 v28, v41 offset:5212
	v_mul_f32_e32 v34, v92, v128
	v_mul_f32_e32 v35, v104, v129
	v_cvt_pk_bf16_f32 v38, v34, v35
	ds_write_b32 v28, v38 offset:6240
	v_mul_f32_e32 v36, v93, v128
	v_mul_f32_e32 v37, v105, v129
	v_cvt_pk_bf16_f32 v39, v36, v37
	ds_write_b32 v28, v39 offset:6244
	v_mul_f32_e32 v34, v94, v128
	v_mul_f32_e32 v35, v106, v129
	v_cvt_pk_bf16_f32 v40, v34, v35
	ds_write_b32 v28, v40 offset:6248
	v_mul_f32_e32 v36, v95, v128
	v_mul_f32_e32 v37, v107, v129
	v_cvt_pk_bf16_f32 v41, v36, v37
	ds_write_b32 v28, v41 offset:6252
	v_mul_f32_e32 v34, v108, v130
	v_mul_f32_e32 v35, v112, v131
	v_cvt_pk_bf16_f32 v38, v34, v35
	ds_write_b32 v28, v38 offset:7280
	v_mul_f32_e32 v36, v109, v130
	v_mul_f32_e32 v37, v113, v131
	v_cvt_pk_bf16_f32 v39, v36, v37
	ds_write_b32 v28, v39 offset:7284
	v_mul_f32_e32 v34, v110, v130
	v_mul_f32_e32 v35, v114, v131
	v_cvt_pk_bf16_f32 v40, v34, v35
	ds_write_b32 v28, v40 offset:7288
	v_mul_f32_e32 v36, v111, v130
	v_mul_f32_e32 v37, v115, v131
	v_cvt_pk_bf16_f32 v41, v36, v37
	ds_write_b32 v28, v41 offset:7292
	s_add_i32 s9, s8, 0x380
	s_cmpk_lt_i32 s9, 0x5600
	s_cbranch_scc0 .Ltrx_noload
	s_mul_hi_u32 s23, s9, 0x2fa0be83
	s_lshr_b32 s23, s23, 6
	s_mul_i32 s25, s23, 0x158
	s_sub_i32 s24, s9, s25
	s_mul_i32 s25, s23, 0x560000
	s_lshl_b32 s33, s24, 8
	s_add_i32 s25, s25, s33
	s_add_u32 s26, s2, s25
	s_addc_u32 s27, s3, 0
	s_lshl_b32 s25, s23, 8
	s_add_u32 s28, s4, s25
	s_addc_u32 s29, s5, 0
	global_load_dwordx4 v[44:47], v0, s[26:27]
	global_load_dwordx4 v[48:51], v1, s[26:27]
	global_load_dwordx4 v[52:55], v2, s[26:27]
	global_load_dwordx4 v[56:59], v3, s[26:27]
	global_load_dwordx4 v[60:63], v4, s[26:27]
	global_load_dwordx4 v[64:67], v5, s[26:27]
	global_load_dwordx4 v[68:71], v6, s[26:27]
	global_load_dwordx4 v[72:75], v7, s[26:27]
	global_load_dwordx4 v[76:79], v8, s[26:27]
	global_load_dwordx4 v[80:83], v9, s[26:27]
	global_load_dwordx4 v[84:87], v10, s[26:27]
	global_load_dwordx4 v[88:91], v11, s[26:27]
	global_load_dwordx4 v[92:95], v16, s[26:27]
	global_load_dwordx4 v[104:107], v17, s[26:27]
	global_load_dwordx4 v[108:111], v18, s[26:27]
	global_load_dwordx4 v[112:115], v19, s[26:27]
	global_load_dwordx2 v[116:117], v30, s[28:29]
	global_load_dwordx2 v[118:119], v30, s[28:29] offset:32
	global_load_dwordx2 v[120:121], v30, s[28:29] offset:64
	global_load_dwordx2 v[122:123], v30, s[28:29] offset:96
	global_load_dwordx2 v[124:125], v30, s[28:29] offset:128
	global_load_dwordx2 v[126:127], v30, s[28:29] offset:160
	global_load_dwordx2 v[128:129], v30, s[28:29] offset:192
	global_load_dwordx2 v[130:131], v30, s[28:29] offset:224

.Ltrx_done:
.LBB0_1867:
	v_readlane_b32 s2, v254, 40
	s_add_i32 s20, s2, 9
	s_cmp_ge_i32 s20, s65
	s_cbranch_scc1 .LBB0_1916
	s_waitcnt vmcnt(0)
	s_waitcnt vmcnt(0) lgkmcnt(0)
	s_barrier
	s_mov_b64 s[2:3], exec
	v_readlane_b32 s4, v253, 27
	v_readlane_b32 s5, v253, 28
	s_and_b64 s[4:5], s[2:3], s[4:5]
	s_mov_b64 exec, s[4:5]
	s_cbranch_execz .LBB0_1915
	v_mov_b32_e32 v0, s79
	s_waitcnt vmcnt(0) expcnt(0) lgkmcnt(0)
	ds_read_b32 v2, v0
	ds_read_b32 v0, v0 offset:4
	s_waitcnt lgkmcnt(1)
	v_cmp_ne_u32_e32 vcc, 0, v2
	s_cbranch_vccnz .LBB0_1883
	v_readlane_b32 s6, v251, 0
	v_readlane_b32 s7, v251, 1
	s_load_dwordx2 s[4:5], s[6:7], 0x4
	s_mov_b32 s12, 0
	s_waitcnt lgkmcnt(0)
	s_mul_i32 s9, s4, s97
	s_mul_i32 s9, s9, s5
	s_branch .LBB0_1872
